# v128 plus epilogue de-serialisation (cheap form): the bf16-residual GEMM epilogues touch all of the wave's residual rows up front so the later serialized loads hit L2
# baseline (speedup 1.0000x reference)
.LBB0_41:
	s_add_u32 s54, s52, 0xffe00080
	s_addc_u32 s55, s53, -1
	s_add_i32 s64, 0, 0x10000
	s_cmpk_eq_i32 s63, 0x7c
	s_cselect_b32 s57, s4, s55
	s_cselect_b32 s56, s5, s54
	s_cselect_b32 s55, s37, s62
	s_cselect_b32 s54, s43, s61
	s_add_i32 s66, 0, 0x14000
	v_add_u32_e32 v156, s64, v163
	v_add_u32_e32 v160, s66, v163
	ds_read_b128 v[134:137], v156
	ds_read_b128 v[138:141], v156 offset:1024
	ds_read_b128 v[152:155], v156 offset:2048
	ds_read_b128 v[156:159], v156 offset:3072
	ds_read_b128 v[166:169], v160
	ds_read_b128 v[170:173], v160 offset:1024
	ds_read_b128 v[174:177], v160 offset:2048
	ds_read_b128 v[178:181], v160 offset:3072
	v_lshl_add_u64 v[160:161], s[52:53], 0, v[150:151]
	s_add_i32 m0, s21, 0xc000
	ds_read_b128 v[182:185], v165
	ds_read_b128 v[186:189], v165 offset:1024
	ds_read_b128 v[198:201], v165 offset:2048
	ds_read_b128 v[202:205], v165 offset:3072
	ds_read_b128 v[206:209], v165 offset:4096
	ds_read_b128 v[210:213], v165 offset:5120
	ds_read_b128 v[214:217], v165 offset:6144
	ds_read_b128 v[236:239], v165 offset:7168
	global_load_lds_dwordx4 v[160:161], off
	v_lshl_add_u64 v[160:161], s[52:53], 0, v[148:149]
	s_add_i32 m0, s21, 0xe000
	s_nop 0
	global_load_lds_dwordx4 v[160:161], off
	s_waitcnt vmcnt(8)
	s_waitcnt lgkmcnt(0)
	s_barrier
	s_setprio 1
	s_waitcnt lgkmcnt(0)
	v_mfma_f32_16x16x32_bf16 v[130:133], v[134:137], v[182:185], v[130:133]
	v_mfma_f32_16x16x32_bf16 v[126:129], v[152:155], v[182:185], v[126:129]
	v_mfma_f32_16x16x32_bf16 v[114:117], v[134:137], v[198:201], v[114:117]
	v_mfma_f32_16x16x32_bf16 v[110:113], v[152:155], v[198:201], v[110:113]
	v_mfma_f32_16x16x32_bf16 v[98:101], v[134:137], v[206:209], v[98:101]
	v_mfma_f32_16x16x32_bf16 v[94:97], v[152:155], v[206:209], v[94:97]
	v_mfma_f32_16x16x32_bf16 v[82:85], v[134:137], v[214:217], v[82:85]
	v_mfma_f32_16x16x32_bf16 v[78:81], v[152:155], v[214:217], v[78:81]
	v_mfma_f32_16x16x32_bf16 v[130:133], v[138:141], v[186:189], v[130:133]
	v_mfma_f32_16x16x32_bf16 v[126:129], v[156:159], v[186:189], v[126:129]
	v_mfma_f32_16x16x32_bf16 v[114:117], v[138:141], v[202:205], v[114:117]
	v_mfma_f32_16x16x32_bf16 v[110:113], v[156:159], v[202:205], v[110:113]
	v_mfma_f32_16x16x32_bf16 v[98:101], v[138:141], v[210:213], v[98:101]
	v_mfma_f32_16x16x32_bf16 v[94:97], v[156:159], v[210:213], v[94:97]
	v_mfma_f32_16x16x32_bf16 v[82:85], v[138:141], v[236:239], v[82:85]
	v_mfma_f32_16x16x32_bf16 v[78:81], v[156:159], v[236:239], v[78:81]
	s_setprio 0
	s_setprio 1
	v_mfma_f32_16x16x32_bf16 v[122:125], v[166:169], v[182:185], v[122:125]
	v_mfma_f32_16x16x32_bf16 v[118:121], v[174:177], v[182:185], v[118:121]
	v_mfma_f32_16x16x32_bf16 v[106:109], v[166:169], v[198:201], v[106:109]
	v_mfma_f32_16x16x32_bf16 v[102:105], v[174:177], v[198:201], v[102:105]
	v_mfma_f32_16x16x32_bf16 v[90:93], v[166:169], v[206:209], v[90:93]
	v_mfma_f32_16x16x32_bf16 v[86:89], v[174:177], v[206:209], v[86:89]
	v_mfma_f32_16x16x32_bf16 v[74:77], v[166:169], v[214:217], v[74:77]
	v_mfma_f32_16x16x32_bf16 v[70:73], v[174:177], v[214:217], v[70:73]
	v_mfma_f32_16x16x32_bf16 v[122:125], v[170:173], v[186:189], v[122:125]
	v_mfma_f32_16x16x32_bf16 v[118:121], v[178:181], v[186:189], v[118:121]
	v_mfma_f32_16x16x32_bf16 v[106:109], v[170:173], v[202:205], v[106:109]
	v_mfma_f32_16x16x32_bf16 v[102:105], v[178:181], v[202:205], v[102:105]
	v_mfma_f32_16x16x32_bf16 v[90:93], v[170:173], v[210:213], v[90:93]
	v_mfma_f32_16x16x32_bf16 v[86:89], v[178:181], v[210:213], v[86:89]
	v_mfma_f32_16x16x32_bf16 v[74:77], v[170:173], v[236:239], v[74:77]
	v_mfma_f32_16x16x32_bf16 v[70:73], v[178:181], v[236:239], v[70:73]
	s_setprio 0
	s_barrier
	s_add_i32 s64, s64, s15
	v_lshl_add_u64 v[160:161], s[54:55], 0, v[190:191]
	s_mov_b32 m0, s64
	ds_read_b128 v[182:185], v165 offset:16384
	ds_read_b128 v[186:189], v165 offset:17408
	ds_read_b128 v[198:201], v165 offset:18432
	ds_read_b128 v[202:205], v165 offset:19456
	ds_read_b128 v[206:209], v165 offset:20480
	ds_read_b128 v[210:213], v165 offset:21504
	ds_read_b128 v[214:217], v165 offset:22528
	ds_read_b128 v[236:239], v165 offset:23552
	global_load_lds_dwordx4 v[160:161], off
	s_add_i32 m0, s64, 0x2000
	s_add_u32 s64, s54, 0x200000
	v_lshl_add_u64 v[218:219], s[54:55], 0, v[146:147]
	s_addc_u32 s65, s55, 0
	s_add_i32 s66, s66, s15
	global_load_lds_dwordx4 v[218:219], off
	v_lshl_add_u64 v[240:241], s[64:65], 0, v[190:191]
	s_mov_b32 m0, s66
	v_lshl_add_u64 v[242:243], s[56:57], 0, v[144:145]
	global_load_lds_dwordx4 v[240:241], off
	v_lshl_add_u64 v[240:241], s[64:65], 0, v[146:147]
	s_add_i32 m0, s66, 0x2000
	s_nop 0
	global_load_lds_dwordx4 v[240:241], off
	v_lshl_add_u64 v[240:241], s[56:57], 0, v[142:143]
	s_mov_b32 m0, s21
	s_nop 0
	global_load_lds_dwordx4 v[240:241], off
	s_mov_b32 m0, s23
	s_nop 0
	global_load_lds_dwordx4 v[242:243], off
	s_waitcnt vmcnt(8)
	s_waitcnt lgkmcnt(0)
	s_barrier
	s_setprio 1
	s_waitcnt lgkmcnt(0)
	v_mfma_f32_16x16x32_bf16 v[66:69], v[134:137], v[182:185], v[66:69]
	v_mfma_f32_16x16x32_bf16 v[62:65], v[152:155], v[182:185], v[62:65]
	v_mfma_f32_16x16x32_bf16 v[50:53], v[134:137], v[198:201], v[50:53]
	v_mfma_f32_16x16x32_bf16 v[46:49], v[152:155], v[198:201], v[46:49]
	v_mfma_f32_16x16x32_bf16 v[34:37], v[134:137], v[206:209], v[34:37]
	v_mfma_f32_16x16x32_bf16 v[30:33], v[152:155], v[206:209], v[30:33]
	v_mfma_f32_16x16x32_bf16 v[18:21], v[134:137], v[214:217], v[18:21]
	v_mfma_f32_16x16x32_bf16 v[14:17], v[152:155], v[214:217], v[14:17]
	v_mfma_f32_16x16x32_bf16 v[66:69], v[138:141], v[186:189], v[66:69]
	v_mfma_f32_16x16x32_bf16 v[62:65], v[156:159], v[186:189], v[62:65]
	v_mfma_f32_16x16x32_bf16 v[50:53], v[138:141], v[202:205], v[50:53]
	v_mfma_f32_16x16x32_bf16 v[46:49], v[156:159], v[202:205], v[46:49]
	v_mfma_f32_16x16x32_bf16 v[34:37], v[138:141], v[210:213], v[34:37]
	v_mfma_f32_16x16x32_bf16 v[30:33], v[156:159], v[210:213], v[30:33]
	v_mfma_f32_16x16x32_bf16 v[18:21], v[138:141], v[236:239], v[18:21]
	v_mfma_f32_16x16x32_bf16 v[14:17], v[156:159], v[236:239], v[14:17]
	s_setprio 0
	s_setprio 1
	v_mfma_f32_16x16x32_bf16 v[58:61], v[166:169], v[182:185], v[58:61]
	v_mfma_f32_16x16x32_bf16 v[54:57], v[174:177], v[182:185], v[54:57]
	v_mfma_f32_16x16x32_bf16 v[42:45], v[166:169], v[198:201], v[42:45]
	v_mfma_f32_16x16x32_bf16 v[38:41], v[174:177], v[198:201], v[38:41]
	v_mfma_f32_16x16x32_bf16 v[26:29], v[166:169], v[206:209], v[26:29]
	v_mfma_f32_16x16x32_bf16 v[22:25], v[174:177], v[206:209], v[22:25]
	v_mfma_f32_16x16x32_bf16 v[10:13], v[166:169], v[214:217], v[10:13]
	v_mfma_f32_16x16x32_bf16 v[6:9], v[174:177], v[214:217], v[6:9]
	v_mfma_f32_16x16x32_bf16 v[58:61], v[170:173], v[186:189], v[58:61]
	v_mfma_f32_16x16x32_bf16 v[54:57], v[178:181], v[186:189], v[54:57]
	v_mfma_f32_16x16x32_bf16 v[42:45], v[170:173], v[202:205], v[42:45]
	v_mfma_f32_16x16x32_bf16 v[38:41], v[178:181], v[202:205], v[38:41]
	v_mfma_f32_16x16x32_bf16 v[26:29], v[170:173], v[210:213], v[26:29]
	v_mfma_f32_16x16x32_bf16 v[22:25], v[178:181], v[210:213], v[22:25]
	v_mfma_f32_16x16x32_bf16 v[10:13], v[170:173], v[236:239], v[10:13]
	v_mfma_f32_16x16x32_bf16 v[6:9], v[178:181], v[236:239], v[6:9]
	s_setprio 0
	s_barrier
	s_add_i32 s64, 0, 0x18000
	s_add_i32 s65, 0, 0x1c000
	v_add_u32_e32 v156, s64, v163
	v_add_u32_e32 v178, s65, v163
	ds_read_b128 v[134:137], v156
	ds_read_b128 v[138:141], v156 offset:1024
	ds_read_b128 v[152:155], v156 offset:2048
	ds_read_b128 v[156:159], v156 offset:3072
	ds_read_b128 v[166:169], v178
	ds_read_b128 v[170:173], v178 offset:1024
	ds_read_b128 v[174:177], v178 offset:2048
	ds_read_b128 v[178:181], v178 offset:3072
	s_add_u32 s56, s56, 0x200000
	s_addc_u32 s57, s57, 0
	s_mov_b32 m0, s26
	v_lshl_add_u64 v[244:245], s[56:57], 0, v[142:143]
	ds_read_b128 v[182:185], v165 offset:32768
	ds_read_b128 v[186:189], v165 offset:33792
	ds_read_b128 v[198:201], v165 offset:34816
	ds_read_b128 v[202:205], v165 offset:35840
	ds_read_b128 v[206:209], v165 offset:36864
	ds_read_b128 v[210:213], v165 offset:37888
	ds_read_b128 v[214:217], v165 offset:38912
	ds_read_b128 v[236:239], v165 offset:39936
	global_load_lds_dwordx4 v[244:245], off
	v_lshl_add_u64 v[244:245], s[56:57], 0, v[144:145]
	s_mov_b32 m0, s29
	s_nop 0
	global_load_lds_dwordx4 v[244:245], off
	s_waitcnt vmcnt(8)
	s_waitcnt lgkmcnt(0)
	s_barrier
	s_setprio 1
	s_waitcnt lgkmcnt(0)
	v_mfma_f32_16x16x32_bf16 v[130:133], v[134:137], v[182:185], v[130:133]
	v_mfma_f32_16x16x32_bf16 v[126:129], v[152:155], v[182:185], v[126:129]
	v_mfma_f32_16x16x32_bf16 v[114:117], v[134:137], v[198:201], v[114:117]
	v_mfma_f32_16x16x32_bf16 v[110:113], v[152:155], v[198:201], v[110:113]
	v_mfma_f32_16x16x32_bf16 v[98:101], v[134:137], v[206:209], v[98:101]
	v_mfma_f32_16x16x32_bf16 v[94:97], v[152:155], v[206:209], v[94:97]
	v_mfma_f32_16x16x32_bf16 v[82:85], v[134:137], v[214:217], v[82:85]
	v_mfma_f32_16x16x32_bf16 v[78:81], v[152:155], v[214:217], v[78:81]
	v_mfma_f32_16x16x32_bf16 v[130:133], v[138:141], v[186:189], v[130:133]
	v_mfma_f32_16x16x32_bf16 v[126:129], v[156:159], v[186:189], v[126:129]
	v_mfma_f32_16x16x32_bf16 v[114:117], v[138:141], v[202:205], v[114:117]
	v_mfma_f32_16x16x32_bf16 v[110:113], v[156:159], v[202:205], v[110:113]
	v_mfma_f32_16x16x32_bf16 v[98:101], v[138:141], v[210:213], v[98:101]
	v_mfma_f32_16x16x32_bf16 v[94:97], v[156:159], v[210:213], v[94:97]
	v_mfma_f32_16x16x32_bf16 v[82:85], v[138:141], v[236:239], v[82:85]
	v_mfma_f32_16x16x32_bf16 v[78:81], v[156:159], v[236:239], v[78:81]
	s_setprio 0
	s_setprio 1
	v_mfma_f32_16x16x32_bf16 v[122:125], v[166:169], v[182:185], v[122:125]
	v_mfma_f32_16x16x32_bf16 v[118:121], v[174:177], v[182:185], v[118:121]
	v_mfma_f32_16x16x32_bf16 v[106:109], v[166:169], v[198:201], v[106:109]
	v_mfma_f32_16x16x32_bf16 v[102:105], v[174:177], v[198:201], v[102:105]
	v_mfma_f32_16x16x32_bf16 v[90:93], v[166:169], v[206:209], v[90:93]
	v_mfma_f32_16x16x32_bf16 v[86:89], v[174:177], v[206:209], v[86:89]
	v_mfma_f32_16x16x32_bf16 v[74:77], v[166:169], v[214:217], v[74:77]
	v_mfma_f32_16x16x32_bf16 v[70:73], v[174:177], v[214:217], v[70:73]
	v_mfma_f32_16x16x32_bf16 v[122:125], v[170:173], v[186:189], v[122:125]
	v_mfma_f32_16x16x32_bf16 v[118:121], v[178:181], v[186:189], v[118:121]
	v_mfma_f32_16x16x32_bf16 v[106:109], v[170:173], v[202:205], v[106:109]
	v_mfma_f32_16x16x32_bf16 v[102:105], v[178:181], v[202:205], v[102:105]
	v_mfma_f32_16x16x32_bf16 v[90:93], v[170:173], v[210:213], v[90:93]
	v_mfma_f32_16x16x32_bf16 v[86:89], v[178:181], v[210:213], v[86:89]
	v_mfma_f32_16x16x32_bf16 v[74:77], v[170:173], v[236:239], v[74:77]
	v_mfma_f32_16x16x32_bf16 v[70:73], v[178:181], v[236:239], v[70:73]
	s_setprio 0
	s_barrier
	s_add_i32 s56, s64, s15
	v_lshl_add_u64 v[160:161], v[160:161], 0, s[30:31]
	s_mov_b32 m0, s56
	ds_read_b128 v[182:185], v165 offset:49152
	ds_read_b128 v[186:189], v165 offset:50176
	ds_read_b128 v[198:201], v165 offset:51200
	ds_read_b128 v[202:205], v165 offset:52224
	ds_read_b128 v[206:209], v165 offset:53248
	ds_read_b128 v[210:213], v165 offset:54272
	ds_read_b128 v[214:217], v165 offset:55296
	ds_read_b128 v[236:239], v165 offset:56320
	global_load_lds_dwordx4 v[160:161], off
	s_add_i32 m0, s56, 0x2000
	s_add_u32 s54, s54, 0x200080
	v_lshl_add_u64 v[160:161], v[218:219], 0, s[30:31]
	s_addc_u32 s55, s55, 0
	s_add_i32 s56, s65, s15
	global_load_lds_dwordx4 v[160:161], off
	v_lshl_add_u64 v[160:161], s[54:55], 0, v[190:191]
	s_mov_b32 m0, s56
	s_nop 0
	global_load_lds_dwordx4 v[160:161], off
	v_lshl_add_u64 v[160:161], s[54:55], 0, v[146:147]
	s_add_i32 m0, s56, 0x2000
	s_nop 0
	global_load_lds_dwordx4 v[160:161], off
	v_lshl_add_u64 v[160:161], v[240:241], 0, s[30:31]
	s_mov_b32 m0, s51
	s_nop 0
	global_load_lds_dwordx4 v[160:161], off
	v_lshl_add_u64 v[160:161], v[242:243], 0, s[30:31]
	s_mov_b32 m0, s58
	s_nop 0
	global_load_lds_dwordx4 v[160:161], off
	s_waitcnt vmcnt(8)
	s_waitcnt lgkmcnt(0)
	s_barrier
	s_setprio 1
	s_waitcnt lgkmcnt(0)
	v_mfma_f32_16x16x32_bf16 v[66:69], v[134:137], v[182:185], v[66:69]
	v_mfma_f32_16x16x32_bf16 v[62:65], v[152:155], v[182:185], v[62:65]
	v_mfma_f32_16x16x32_bf16 v[50:53], v[134:137], v[198:201], v[50:53]
	v_mfma_f32_16x16x32_bf16 v[46:49], v[152:155], v[198:201], v[46:49]
	v_mfma_f32_16x16x32_bf16 v[34:37], v[134:137], v[206:209], v[34:37]
	v_mfma_f32_16x16x32_bf16 v[30:33], v[152:155], v[206:209], v[30:33]
	v_mfma_f32_16x16x32_bf16 v[18:21], v[134:137], v[214:217], v[18:21]
	v_mfma_f32_16x16x32_bf16 v[14:17], v[152:155], v[214:217], v[14:17]
	v_mfma_f32_16x16x32_bf16 v[66:69], v[138:141], v[186:189], v[66:69]
	v_mfma_f32_16x16x32_bf16 v[62:65], v[156:159], v[186:189], v[62:65]
	v_mfma_f32_16x16x32_bf16 v[50:53], v[138:141], v[202:205], v[50:53]
	v_mfma_f32_16x16x32_bf16 v[46:49], v[156:159], v[202:205], v[46:49]
	v_mfma_f32_16x16x32_bf16 v[34:37], v[138:141], v[210:213], v[34:37]
	v_mfma_f32_16x16x32_bf16 v[30:33], v[156:159], v[210:213], v[30:33]
	v_mfma_f32_16x16x32_bf16 v[18:21], v[138:141], v[236:239], v[18:21]
	v_mfma_f32_16x16x32_bf16 v[14:17], v[156:159], v[236:239], v[14:17]
	s_setprio 0
	s_setprio 1
	v_mfma_f32_16x16x32_bf16 v[58:61], v[166:169], v[182:185], v[58:61]
	v_mfma_f32_16x16x32_bf16 v[54:57], v[174:177], v[182:185], v[54:57]
	v_mfma_f32_16x16x32_bf16 v[42:45], v[166:169], v[198:201], v[42:45]
	v_mfma_f32_16x16x32_bf16 v[38:41], v[174:177], v[198:201], v[38:41]
	v_mfma_f32_16x16x32_bf16 v[26:29], v[166:169], v[206:209], v[26:29]
	v_mfma_f32_16x16x32_bf16 v[22:25], v[174:177], v[206:209], v[22:25]
	v_mfma_f32_16x16x32_bf16 v[10:13], v[166:169], v[214:217], v[10:13]
	v_mfma_f32_16x16x32_bf16 v[6:9], v[174:177], v[214:217], v[6:9]
	v_mfma_f32_16x16x32_bf16 v[58:61], v[170:173], v[186:189], v[58:61]
	v_mfma_f32_16x16x32_bf16 v[54:57], v[178:181], v[186:189], v[54:57]
	v_mfma_f32_16x16x32_bf16 v[42:45], v[170:173], v[202:205], v[42:45]
	v_mfma_f32_16x16x32_bf16 v[38:41], v[178:181], v[202:205], v[38:41]
	v_mfma_f32_16x16x32_bf16 v[26:29], v[170:173], v[210:213], v[26:29]
	v_mfma_f32_16x16x32_bf16 v[22:25], v[178:181], v[210:213], v[22:25]
	v_mfma_f32_16x16x32_bf16 v[10:13], v[170:173], v[236:239], v[10:13]
	v_mfma_f32_16x16x32_bf16 v[6:9], v[178:181], v[236:239], v[6:9]
	s_setprio 0
	s_barrier
	s_add_i32 s63, s63, 2
	s_add_u32 s61, s61, 0x100
	s_addc_u32 s62, s62, 0
	s_add_u32 s52, s52, 0x100
	s_addc_u32 s53, s53, 0
	s_cmpk_gt_u32 s63, 0x7d
	s_cbranch_scc0 .LBB0_41
	v_lshl_or_b32 v152, s50, 8, v164
	v_lshl_add_u32 v154, s48, 8, v162
	v_ashrrev_i32_e32 v153, 31, v152
	v_readlane_b32 s4, v255, 14
	v_ashrrev_i32_e32 v155, 31, v154
	v_lshlrev_b64 v[176:177], 1, v[152:153]
	v_readlane_b32 s5, v255, 15
	v_lshlrev_b64 v[158:159], 12, v[154:155]
	v_or_b32_e32 v160, 16, v154
	v_lshl_add_u64 v[156:157], s[4:5], 0, v[176:177]
	v_lshl_add_u64 v[134:135], v[156:157], 0, v[158:159]
	global_load_dwordx4 v[168:171], v[134:135], off
	global_load_dwordx4 v[172:175], v[134:135], off offset:256
	v_ashrrev_i32_e32 v161, 31, v160
	v_lshlrev_b64 v[134:135], 12, v[160:161]
	v_lshl_add_u64 v[134:135], v[156:157], 0, v[134:135]
	global_load_dwordx4 v[138:141], v[134:135], off
	s_nop 0
	global_load_dwordx4 v[134:137], v[134:135], off offset:256
	v_lshl_add_u64 v[246:247], v[156:157], 0, v[158:159]
	v_add_co_u32_e32 v248, vcc, 0x20000, v246
	s_nop 1
	v_addc_co_u32_e32 v249, vcc, 0, v247, vcc
	global_load_dword v250, v[248:249], off
	global_load_dword v250, v[248:249], off offset:256
	v_add_co_u32_e32 v248, vcc, 0x30000, v246
	s_nop 1
	v_addc_co_u32_e32 v249, vcc, 0, v247, vcc
	global_load_dword v250, v[248:249], off
	global_load_dword v250, v[248:249], off offset:256
	v_add_co_u32_e32 v248, vcc, 0x80000, v246
	s_nop 1
	v_addc_co_u32_e32 v249, vcc, 0, v247, vcc
	global_load_dword v250, v[248:249], off
	global_load_dword v250, v[248:249], off offset:256
	v_add_co_u32_e32 v248, vcc, 0x90000, v246
	s_nop 1
	v_addc_co_u32_e32 v249, vcc, 0, v247, vcc
	global_load_dword v250, v[248:249], off
	global_load_dword v250, v[248:249], off offset:256
	v_add_co_u32_e32 v248, vcc, 0xa0000, v246
	s_nop 1
	v_addc_co_u32_e32 v249, vcc, 0, v247, vcc
	global_load_dword v250, v[248:249], off
	global_load_dword v250, v[248:249], off offset:256
	v_add_co_u32_e32 v248, vcc, 0xb0000, v246
	s_nop 1
	v_addc_co_u32_e32 v249, vcc, 0, v247, vcc
	global_load_dword v250, v[248:249], off
	global_load_dword v250, v[248:249], off offset:256
	v_and_b32_e32 v167, 64, v221
	v_xor_b32_e32 v166, 16, v221
	v_add_u32_e32 v167, 64, v167
	v_xor_b32_e32 v178, 32, v221
	v_cmp_lt_i32_e32 vcc, v166, v167
	s_waitcnt vmcnt(0)
	v_lshlrev_b32_e32 v180, 16, v170
	v_cndmask_b32_e32 v166, v221, v166, vcc
	v_cmp_lt_i32_e32 vcc, v178, v167
	v_and_b32_e32 v181, 0xffff0000, v170
	v_lshlrev_b32_e32 v170, 16, v171
	v_cndmask_b32_e32 v167, v221, v178, vcc
	v_lshl_add_u64 v[178:179], s[4:5], 0, v[158:159]
	v_lshl_add_u64 v[176:177], v[178:179], 0, v[176:177]
	v_lshlrev_b32_e32 v178, 16, v168
	v_and_b32_e32 v179, 0xffff0000, v168
	v_lshlrev_b32_e32 v168, 16, v169
	v_and_b32_e32 v169, 0xffff0000, v169
	v_and_b32_e32 v171, 0xffff0000, v171
	v_lshlrev_b32_e32 v182, 16, v172
	v_and_b32_e32 v183, 0xffff0000, v172
	v_lshlrev_b32_e32 v172, 16, v173
	v_and_b32_e32 v173, 0xffff0000, v173
	v_lshlrev_b32_e32 v184, 16, v174
	v_and_b32_e32 v185, 0xffff0000, v174
	v_lshlrev_b32_e32 v174, 16, v175
	v_and_b32_e32 v175, 0xffff0000, v175
	v_pk_add_f32 v[132:133], v[132:133], v[168:169]
	v_pk_add_f32 v[130:131], v[130:131], v[178:179]
	v_pk_add_f32 v[128:129], v[128:129], v[170:171]
	v_pk_add_f32 v[126:127], v[126:127], v[180:181]
	v_pk_add_f32 v[168:169], v[124:125], v[172:173]
	v_pk_add_f32 v[122:123], v[122:123], v[182:183]
	v_pk_add_f32 v[170:171], v[120:121], v[174:175]
	v_pk_add_f32 v[172:173], v[118:119], v[184:185]
	v_mul_f32_e32 v121, v131, v131
	v_mul_f32_e32 v124, v133, v133
	v_mul_f32_e32 v125, v127, v127
	v_mul_f32_e32 v174, v129, v129
	v_cvt_pk_bf16_f32 v118, v130, v131
	v_cvt_pk_bf16_f32 v119, v132, v133
	v_cvt_pk_bf16_f32 v120, v126, v127
	v_mul_f32_e32 v127, v123, v123
	v_mul_f32_e32 v131, v169, v169
	v_mul_f32_e32 v133, v173, v173
	v_mul_f32_e32 v175, v171, v171
	v_fmac_f32_e32 v121, v130, v130
	v_fmac_f32_e32 v124, v132, v132
	v_fmac_f32_e32 v125, v126, v126
	v_fmac_f32_e32 v174, v128, v128
	v_fmac_f32_e32 v127, v122, v122
	v_fmac_f32_e32 v131, v168, v168
	v_fmac_f32_e32 v133, v172, v172
	v_fmac_f32_e32 v175, v170, v170
	v_add_f32_e32 v121, v121, v124
	v_add_f32_e32 v124, v125, v174
	v_add_f32_e32 v125, v127, v131
	v_add_f32_e32 v126, v133, v175
	v_add_f32_e32 v121, v121, v124
	v_add_f32_e32 v124, v125, v126
	v_lshlrev_b32_e32 v166, 2, v166
	v_add_f32_e32 v126, v121, v124
	ds_bpermute_b32 v127, v166, v126
	v_cvt_pk_bf16_f32 v121, v128, v129
	global_store_dwordx4 v[176:177], v[118:121], off
	v_cvt_pk_bf16_f32 v124, v122, v123
	v_cvt_pk_bf16_f32 v125, v168, v169
	s_waitcnt lgkmcnt(0)
	s_nop 0
	v_add_f32_e32 v121, v126, v127
	v_lshlrev_b32_e32 v120, 2, v167
	ds_bpermute_b32 v122, v120, v121
	v_lshl_add_u64 v[118:119], v[154:155], 3, s[18:19]
	v_cvt_pk_bf16_f32 v126, v172, v173
	v_cvt_pk_bf16_f32 v127, v170, v171
	global_store_dwordx4 v[176:177], v[124:127], off offset:256
	s_and_saveexec_b64 s[4:5], s[38:39]
	s_cbranch_execz .LBB0_44
	s_waitcnt lgkmcnt(0)
	v_add_f32_e32 v121, v121, v122
	v_mul_f32_e32 v121, 0x4b800000, v121
	v_trunc_f32_e32 v121, v121
	v_mul_f32_e32 v122, 0x2f800000, v121
	v_floor_f32_e32 v123, v122
	v_fmac_f32_e32 v121, 0xcf800000, v123
	v_cvt_u32_f32_e32 v122, v121
	v_cvt_u32_f32_e32 v123, v123
	global_atomic_add_x2 v[118:119], v[122:123], off

.LBB0_110:
	s_add_u32 s54, s52, 0xfff80080
	s_addc_u32 s55, s53, -1
	s_add_i32 s64, 0, 0x10000
	s_cmp_eq_u32 s63, 28
	s_cselect_b32 s57, s4, s55
	s_cselect_b32 s56, s5, s54
	s_cselect_b32 s55, s37, s62
	s_cselect_b32 s54, s43, s61
	s_add_i32 s66, 0, 0x14000
	v_add_u32_e32 v156, s64, v163
	v_add_u32_e32 v160, s66, v163
	ds_read_b128 v[134:137], v156
	ds_read_b128 v[138:141], v156 offset:1024
	ds_read_b128 v[152:155], v156 offset:2048
	ds_read_b128 v[156:159], v156 offset:3072
	ds_read_b128 v[166:169], v160
	ds_read_b128 v[170:173], v160 offset:1024
	ds_read_b128 v[174:177], v160 offset:2048
	ds_read_b128 v[178:181], v160 offset:3072
	v_lshl_add_u64 v[160:161], s[52:53], 0, v[150:151]
	s_add_i32 m0, s21, 0xc000
	ds_read_b128 v[182:185], v165
	ds_read_b128 v[186:189], v165 offset:1024
	ds_read_b128 v[198:201], v165 offset:2048
	ds_read_b128 v[202:205], v165 offset:3072
	ds_read_b128 v[206:209], v165 offset:4096
	ds_read_b128 v[210:213], v165 offset:5120
	ds_read_b128 v[214:217], v165 offset:6144
	ds_read_b128 v[236:239], v165 offset:7168
	global_load_lds_dwordx4 v[160:161], off
	v_lshl_add_u64 v[160:161], s[52:53], 0, v[148:149]
	s_add_i32 m0, s21, 0xe000
	s_nop 0
	global_load_lds_dwordx4 v[160:161], off
	s_waitcnt vmcnt(8)
	s_waitcnt lgkmcnt(0)
	s_barrier
	s_setprio 1
	s_waitcnt lgkmcnt(0)
	v_mfma_f32_16x16x32_bf16 v[130:133], v[134:137], v[182:185], v[130:133]
	v_mfma_f32_16x16x32_bf16 v[126:129], v[152:155], v[182:185], v[126:129]
	v_mfma_f32_16x16x32_bf16 v[114:117], v[134:137], v[198:201], v[114:117]
	v_mfma_f32_16x16x32_bf16 v[110:113], v[152:155], v[198:201], v[110:113]
	v_mfma_f32_16x16x32_bf16 v[98:101], v[134:137], v[206:209], v[98:101]
	v_mfma_f32_16x16x32_bf16 v[94:97], v[152:155], v[206:209], v[94:97]
	v_mfma_f32_16x16x32_bf16 v[82:85], v[134:137], v[214:217], v[82:85]
	v_mfma_f32_16x16x32_bf16 v[78:81], v[152:155], v[214:217], v[78:81]
	v_mfma_f32_16x16x32_bf16 v[130:133], v[138:141], v[186:189], v[130:133]
	v_mfma_f32_16x16x32_bf16 v[126:129], v[156:159], v[186:189], v[126:129]
	v_mfma_f32_16x16x32_bf16 v[114:117], v[138:141], v[202:205], v[114:117]
	v_mfma_f32_16x16x32_bf16 v[110:113], v[156:159], v[202:205], v[110:113]
	v_mfma_f32_16x16x32_bf16 v[98:101], v[138:141], v[210:213], v[98:101]
	v_mfma_f32_16x16x32_bf16 v[94:97], v[156:159], v[210:213], v[94:97]
	v_mfma_f32_16x16x32_bf16 v[82:85], v[138:141], v[236:239], v[82:85]
	v_mfma_f32_16x16x32_bf16 v[78:81], v[156:159], v[236:239], v[78:81]
	s_setprio 0
	s_setprio 1
	v_mfma_f32_16x16x32_bf16 v[122:125], v[166:169], v[182:185], v[122:125]
	v_mfma_f32_16x16x32_bf16 v[118:121], v[174:177], v[182:185], v[118:121]
	v_mfma_f32_16x16x32_bf16 v[106:109], v[166:169], v[198:201], v[106:109]
	v_mfma_f32_16x16x32_bf16 v[102:105], v[174:177], v[198:201], v[102:105]
	v_mfma_f32_16x16x32_bf16 v[90:93], v[166:169], v[206:209], v[90:93]
	v_mfma_f32_16x16x32_bf16 v[86:89], v[174:177], v[206:209], v[86:89]
	v_mfma_f32_16x16x32_bf16 v[74:77], v[166:169], v[214:217], v[74:77]
	v_mfma_f32_16x16x32_bf16 v[70:73], v[174:177], v[214:217], v[70:73]
	v_mfma_f32_16x16x32_bf16 v[122:125], v[170:173], v[186:189], v[122:125]
	v_mfma_f32_16x16x32_bf16 v[118:121], v[178:181], v[186:189], v[118:121]
	v_mfma_f32_16x16x32_bf16 v[106:109], v[170:173], v[202:205], v[106:109]
	v_mfma_f32_16x16x32_bf16 v[102:105], v[178:181], v[202:205], v[102:105]
	v_mfma_f32_16x16x32_bf16 v[90:93], v[170:173], v[210:213], v[90:93]
	v_mfma_f32_16x16x32_bf16 v[86:89], v[178:181], v[210:213], v[86:89]
	v_mfma_f32_16x16x32_bf16 v[74:77], v[170:173], v[236:239], v[74:77]
	v_mfma_f32_16x16x32_bf16 v[70:73], v[178:181], v[236:239], v[70:73]
	s_setprio 0
	s_barrier
	s_add_i32 s64, s64, s15
	v_lshl_add_u64 v[160:161], s[54:55], 0, v[190:191]
	s_mov_b32 m0, s64
	ds_read_b128 v[182:185], v165 offset:16384
	ds_read_b128 v[186:189], v165 offset:17408
	ds_read_b128 v[198:201], v165 offset:18432
	ds_read_b128 v[202:205], v165 offset:19456
	ds_read_b128 v[206:209], v165 offset:20480
	ds_read_b128 v[210:213], v165 offset:21504
	ds_read_b128 v[214:217], v165 offset:22528
	ds_read_b128 v[236:239], v165 offset:23552
	global_load_lds_dwordx4 v[160:161], off
	s_add_i32 m0, s64, 0x2000
	s_add_u32 s64, s54, 0x80000
	v_lshl_add_u64 v[218:219], s[54:55], 0, v[146:147]
	s_addc_u32 s65, s55, 0
	s_add_i32 s66, s66, s15
	global_load_lds_dwordx4 v[218:219], off
	v_lshl_add_u64 v[240:241], s[64:65], 0, v[190:191]
	s_mov_b32 m0, s66
	v_lshl_add_u64 v[242:243], s[56:57], 0, v[144:145]
	global_load_lds_dwordx4 v[240:241], off
	v_lshl_add_u64 v[240:241], s[64:65], 0, v[146:147]
	s_add_i32 m0, s66, 0x2000
	s_nop 0
	global_load_lds_dwordx4 v[240:241], off
	v_lshl_add_u64 v[240:241], s[56:57], 0, v[142:143]
	s_mov_b32 m0, s21
	s_nop 0
	global_load_lds_dwordx4 v[240:241], off
	s_mov_b32 m0, s23
	s_nop 0
	global_load_lds_dwordx4 v[242:243], off
	s_waitcnt vmcnt(8)
	s_waitcnt lgkmcnt(0)
	s_barrier
	s_setprio 1
	s_waitcnt lgkmcnt(0)
	v_mfma_f32_16x16x32_bf16 v[66:69], v[134:137], v[182:185], v[66:69]
	v_mfma_f32_16x16x32_bf16 v[62:65], v[152:155], v[182:185], v[62:65]
	v_mfma_f32_16x16x32_bf16 v[50:53], v[134:137], v[198:201], v[50:53]
	v_mfma_f32_16x16x32_bf16 v[46:49], v[152:155], v[198:201], v[46:49]
	v_mfma_f32_16x16x32_bf16 v[34:37], v[134:137], v[206:209], v[34:37]
	v_mfma_f32_16x16x32_bf16 v[30:33], v[152:155], v[206:209], v[30:33]
	v_mfma_f32_16x16x32_bf16 v[18:21], v[134:137], v[214:217], v[18:21]
	v_mfma_f32_16x16x32_bf16 v[14:17], v[152:155], v[214:217], v[14:17]
	v_mfma_f32_16x16x32_bf16 v[66:69], v[138:141], v[186:189], v[66:69]
	v_mfma_f32_16x16x32_bf16 v[62:65], v[156:159], v[186:189], v[62:65]
	v_mfma_f32_16x16x32_bf16 v[50:53], v[138:141], v[202:205], v[50:53]
	v_mfma_f32_16x16x32_bf16 v[46:49], v[156:159], v[202:205], v[46:49]
	v_mfma_f32_16x16x32_bf16 v[34:37], v[138:141], v[210:213], v[34:37]
	v_mfma_f32_16x16x32_bf16 v[30:33], v[156:159], v[210:213], v[30:33]
	v_mfma_f32_16x16x32_bf16 v[18:21], v[138:141], v[236:239], v[18:21]
	v_mfma_f32_16x16x32_bf16 v[14:17], v[156:159], v[236:239], v[14:17]
	s_setprio 0
	s_setprio 1
	v_mfma_f32_16x16x32_bf16 v[58:61], v[166:169], v[182:185], v[58:61]
	v_mfma_f32_16x16x32_bf16 v[54:57], v[174:177], v[182:185], v[54:57]
	v_mfma_f32_16x16x32_bf16 v[42:45], v[166:169], v[198:201], v[42:45]
	v_mfma_f32_16x16x32_bf16 v[38:41], v[174:177], v[198:201], v[38:41]
	v_mfma_f32_16x16x32_bf16 v[26:29], v[166:169], v[206:209], v[26:29]
	v_mfma_f32_16x16x32_bf16 v[22:25], v[174:177], v[206:209], v[22:25]
	v_mfma_f32_16x16x32_bf16 v[10:13], v[166:169], v[214:217], v[10:13]
	v_mfma_f32_16x16x32_bf16 v[6:9], v[174:177], v[214:217], v[6:9]
	v_mfma_f32_16x16x32_bf16 v[58:61], v[170:173], v[186:189], v[58:61]
	v_mfma_f32_16x16x32_bf16 v[54:57], v[178:181], v[186:189], v[54:57]
	v_mfma_f32_16x16x32_bf16 v[42:45], v[170:173], v[202:205], v[42:45]
	v_mfma_f32_16x16x32_bf16 v[38:41], v[178:181], v[202:205], v[38:41]
	v_mfma_f32_16x16x32_bf16 v[26:29], v[170:173], v[210:213], v[26:29]
	v_mfma_f32_16x16x32_bf16 v[22:25], v[178:181], v[210:213], v[22:25]
	v_mfma_f32_16x16x32_bf16 v[10:13], v[170:173], v[236:239], v[10:13]
	v_mfma_f32_16x16x32_bf16 v[6:9], v[178:181], v[236:239], v[6:9]
	s_setprio 0
	s_barrier
	s_add_i32 s64, 0, 0x18000
	s_add_i32 s65, 0, 0x1c000
	v_add_u32_e32 v156, s64, v163
	v_add_u32_e32 v178, s65, v163
	ds_read_b128 v[134:137], v156
	ds_read_b128 v[138:141], v156 offset:1024
	ds_read_b128 v[152:155], v156 offset:2048
	ds_read_b128 v[156:159], v156 offset:3072
	ds_read_b128 v[166:169], v178
	ds_read_b128 v[170:173], v178 offset:1024
	ds_read_b128 v[174:177], v178 offset:2048
	ds_read_b128 v[178:181], v178 offset:3072
	s_add_u32 s56, s56, 0x80000
	s_addc_u32 s57, s57, 0
	s_mov_b32 m0, s26
	v_lshl_add_u64 v[244:245], s[56:57], 0, v[142:143]
	ds_read_b128 v[182:185], v165 offset:32768
	ds_read_b128 v[186:189], v165 offset:33792
	ds_read_b128 v[198:201], v165 offset:34816
	ds_read_b128 v[202:205], v165 offset:35840
	ds_read_b128 v[206:209], v165 offset:36864
	ds_read_b128 v[210:213], v165 offset:37888
	ds_read_b128 v[214:217], v165 offset:38912
	ds_read_b128 v[236:239], v165 offset:39936
	global_load_lds_dwordx4 v[244:245], off
	v_lshl_add_u64 v[244:245], s[56:57], 0, v[144:145]
	s_mov_b32 m0, s29
	s_nop 0
	global_load_lds_dwordx4 v[244:245], off
	s_waitcnt vmcnt(8)
	s_waitcnt lgkmcnt(0)
	s_barrier
	s_setprio 1
	s_waitcnt lgkmcnt(0)
	v_mfma_f32_16x16x32_bf16 v[130:133], v[134:137], v[182:185], v[130:133]
	v_mfma_f32_16x16x32_bf16 v[126:129], v[152:155], v[182:185], v[126:129]
	v_mfma_f32_16x16x32_bf16 v[114:117], v[134:137], v[198:201], v[114:117]
	v_mfma_f32_16x16x32_bf16 v[110:113], v[152:155], v[198:201], v[110:113]
	v_mfma_f32_16x16x32_bf16 v[98:101], v[134:137], v[206:209], v[98:101]
	v_mfma_f32_16x16x32_bf16 v[94:97], v[152:155], v[206:209], v[94:97]
	v_mfma_f32_16x16x32_bf16 v[82:85], v[134:137], v[214:217], v[82:85]
	v_mfma_f32_16x16x32_bf16 v[78:81], v[152:155], v[214:217], v[78:81]
	v_mfma_f32_16x16x32_bf16 v[130:133], v[138:141], v[186:189], v[130:133]
	v_mfma_f32_16x16x32_bf16 v[126:129], v[156:159], v[186:189], v[126:129]
	v_mfma_f32_16x16x32_bf16 v[114:117], v[138:141], v[202:205], v[114:117]
	v_mfma_f32_16x16x32_bf16 v[110:113], v[156:159], v[202:205], v[110:113]
	v_mfma_f32_16x16x32_bf16 v[98:101], v[138:141], v[210:213], v[98:101]
	v_mfma_f32_16x16x32_bf16 v[94:97], v[156:159], v[210:213], v[94:97]
	v_mfma_f32_16x16x32_bf16 v[82:85], v[138:141], v[236:239], v[82:85]
	v_mfma_f32_16x16x32_bf16 v[78:81], v[156:159], v[236:239], v[78:81]
	s_setprio 0
	s_setprio 1
	v_mfma_f32_16x16x32_bf16 v[122:125], v[166:169], v[182:185], v[122:125]
	v_mfma_f32_16x16x32_bf16 v[118:121], v[174:177], v[182:185], v[118:121]
	v_mfma_f32_16x16x32_bf16 v[106:109], v[166:169], v[198:201], v[106:109]
	v_mfma_f32_16x16x32_bf16 v[102:105], v[174:177], v[198:201], v[102:105]
	v_mfma_f32_16x16x32_bf16 v[90:93], v[166:169], v[206:209], v[90:93]
	v_mfma_f32_16x16x32_bf16 v[86:89], v[174:177], v[206:209], v[86:89]
	v_mfma_f32_16x16x32_bf16 v[74:77], v[166:169], v[214:217], v[74:77]
	v_mfma_f32_16x16x32_bf16 v[70:73], v[174:177], v[214:217], v[70:73]
	v_mfma_f32_16x16x32_bf16 v[122:125], v[170:173], v[186:189], v[122:125]
	v_mfma_f32_16x16x32_bf16 v[118:121], v[178:181], v[186:189], v[118:121]
	v_mfma_f32_16x16x32_bf16 v[106:109], v[170:173], v[202:205], v[106:109]
	v_mfma_f32_16x16x32_bf16 v[102:105], v[178:181], v[202:205], v[102:105]
	v_mfma_f32_16x16x32_bf16 v[90:93], v[170:173], v[210:213], v[90:93]
	v_mfma_f32_16x16x32_bf16 v[86:89], v[178:181], v[210:213], v[86:89]
	v_mfma_f32_16x16x32_bf16 v[74:77], v[170:173], v[236:239], v[74:77]
	v_mfma_f32_16x16x32_bf16 v[70:73], v[178:181], v[236:239], v[70:73]
	s_setprio 0
	s_barrier
	s_add_i32 s56, s64, s15
	v_lshl_add_u64 v[160:161], v[160:161], 0, s[30:31]
	s_mov_b32 m0, s56
	ds_read_b128 v[182:185], v165 offset:49152
	ds_read_b128 v[186:189], v165 offset:50176
	ds_read_b128 v[198:201], v165 offset:51200
	ds_read_b128 v[202:205], v165 offset:52224
	ds_read_b128 v[206:209], v165 offset:53248
	ds_read_b128 v[210:213], v165 offset:54272
	ds_read_b128 v[214:217], v165 offset:55296
	ds_read_b128 v[236:239], v165 offset:56320
	global_load_lds_dwordx4 v[160:161], off
	s_add_i32 m0, s56, 0x2000
	s_add_u32 s54, s54, 0x80080
	v_lshl_add_u64 v[160:161], v[218:219], 0, s[30:31]
	s_addc_u32 s55, s55, 0
	s_add_i32 s56, s65, s15
	global_load_lds_dwordx4 v[160:161], off
	v_lshl_add_u64 v[160:161], s[54:55], 0, v[190:191]
	s_mov_b32 m0, s56
	s_nop 0
	global_load_lds_dwordx4 v[160:161], off
	v_lshl_add_u64 v[160:161], s[54:55], 0, v[146:147]
	s_add_i32 m0, s56, 0x2000
	s_nop 0
	global_load_lds_dwordx4 v[160:161], off
	v_lshl_add_u64 v[160:161], v[240:241], 0, s[30:31]
	s_mov_b32 m0, s51
	s_nop 0
	global_load_lds_dwordx4 v[160:161], off
	v_lshl_add_u64 v[160:161], v[242:243], 0, s[30:31]
	s_mov_b32 m0, s58
	s_nop 0
	global_load_lds_dwordx4 v[160:161], off
	s_waitcnt vmcnt(8)
	s_waitcnt lgkmcnt(0)
	s_barrier
	s_setprio 1
	s_waitcnt lgkmcnt(0)
	v_mfma_f32_16x16x32_bf16 v[66:69], v[134:137], v[182:185], v[66:69]
	v_mfma_f32_16x16x32_bf16 v[62:65], v[152:155], v[182:185], v[62:65]
	v_mfma_f32_16x16x32_bf16 v[50:53], v[134:137], v[198:201], v[50:53]
	v_mfma_f32_16x16x32_bf16 v[46:49], v[152:155], v[198:201], v[46:49]
	v_mfma_f32_16x16x32_bf16 v[34:37], v[134:137], v[206:209], v[34:37]
	v_mfma_f32_16x16x32_bf16 v[30:33], v[152:155], v[206:209], v[30:33]
	v_mfma_f32_16x16x32_bf16 v[18:21], v[134:137], v[214:217], v[18:21]
	v_mfma_f32_16x16x32_bf16 v[14:17], v[152:155], v[214:217], v[14:17]
	v_mfma_f32_16x16x32_bf16 v[66:69], v[138:141], v[186:189], v[66:69]
	v_mfma_f32_16x16x32_bf16 v[62:65], v[156:159], v[186:189], v[62:65]
	v_mfma_f32_16x16x32_bf16 v[50:53], v[138:141], v[202:205], v[50:53]
	v_mfma_f32_16x16x32_bf16 v[46:49], v[156:159], v[202:205], v[46:49]
	v_mfma_f32_16x16x32_bf16 v[34:37], v[138:141], v[210:213], v[34:37]
	v_mfma_f32_16x16x32_bf16 v[30:33], v[156:159], v[210:213], v[30:33]
	v_mfma_f32_16x16x32_bf16 v[18:21], v[138:141], v[236:239], v[18:21]
	v_mfma_f32_16x16x32_bf16 v[14:17], v[156:159], v[236:239], v[14:17]
	s_setprio 0
	s_setprio 1
	v_mfma_f32_16x16x32_bf16 v[58:61], v[166:169], v[182:185], v[58:61]
	v_mfma_f32_16x16x32_bf16 v[54:57], v[174:177], v[182:185], v[54:57]
	v_mfma_f32_16x16x32_bf16 v[42:45], v[166:169], v[198:201], v[42:45]
	v_mfma_f32_16x16x32_bf16 v[38:41], v[174:177], v[198:201], v[38:41]
	v_mfma_f32_16x16x32_bf16 v[26:29], v[166:169], v[206:209], v[26:29]
	v_mfma_f32_16x16x32_bf16 v[22:25], v[174:177], v[206:209], v[22:25]
	v_mfma_f32_16x16x32_bf16 v[10:13], v[166:169], v[214:217], v[10:13]
	v_mfma_f32_16x16x32_bf16 v[6:9], v[174:177], v[214:217], v[6:9]
	v_mfma_f32_16x16x32_bf16 v[58:61], v[170:173], v[186:189], v[58:61]
	v_mfma_f32_16x16x32_bf16 v[54:57], v[178:181], v[186:189], v[54:57]
	v_mfma_f32_16x16x32_bf16 v[42:45], v[170:173], v[202:205], v[42:45]
	v_mfma_f32_16x16x32_bf16 v[38:41], v[178:181], v[202:205], v[38:41]
	v_mfma_f32_16x16x32_bf16 v[26:29], v[170:173], v[210:213], v[26:29]
	v_mfma_f32_16x16x32_bf16 v[22:25], v[178:181], v[210:213], v[22:25]
	v_mfma_f32_16x16x32_bf16 v[10:13], v[170:173], v[236:239], v[10:13]
	v_mfma_f32_16x16x32_bf16 v[6:9], v[178:181], v[236:239], v[6:9]
	s_setprio 0
	s_barrier
	s_add_i32 s63, s63, 2
	s_add_u32 s61, s61, 0x100
	s_addc_u32 s62, s62, 0
	s_add_u32 s52, s52, 0x100
	s_addc_u32 s53, s53, 0
	s_cmp_gt_u32 s63, 29
	s_cbranch_scc0 .LBB0_110
	v_lshl_or_b32 v152, s50, 8, v164
	v_lshl_add_u32 v154, s48, 8, v162
	v_ashrrev_i32_e32 v153, 31, v152
	v_readlane_b32 s4, v255, 14
	v_ashrrev_i32_e32 v155, 31, v154
	v_lshlrev_b64 v[176:177], 1, v[152:153]
	v_readlane_b32 s5, v255, 15
	v_lshlrev_b64 v[158:159], 12, v[154:155]
	v_or_b32_e32 v160, 16, v154
	v_lshl_add_u64 v[156:157], s[4:5], 0, v[176:177]
	v_lshl_add_u64 v[134:135], v[156:157], 0, v[158:159]
	global_load_dwordx4 v[168:171], v[134:135], off
	global_load_dwordx4 v[172:175], v[134:135], off offset:256
	v_ashrrev_i32_e32 v161, 31, v160
	v_lshlrev_b64 v[134:135], 12, v[160:161]
	v_lshl_add_u64 v[134:135], v[156:157], 0, v[134:135]
	global_load_dwordx4 v[138:141], v[134:135], off
	s_nop 0
	global_load_dwordx4 v[134:137], v[134:135], off offset:256
	v_lshl_add_u64 v[246:247], v[156:157], 0, v[158:159]
	v_add_co_u32_e32 v248, vcc, 0x20000, v246
	s_nop 1
	v_addc_co_u32_e32 v249, vcc, 0, v247, vcc
	global_load_dword v250, v[248:249], off
	global_load_dword v250, v[248:249], off offset:256
	v_add_co_u32_e32 v248, vcc, 0x30000, v246
	s_nop 1
	v_addc_co_u32_e32 v249, vcc, 0, v247, vcc
	global_load_dword v250, v[248:249], off
	global_load_dword v250, v[248:249], off offset:256
	v_add_co_u32_e32 v248, vcc, 0x80000, v246
	s_nop 1
	v_addc_co_u32_e32 v249, vcc, 0, v247, vcc
	global_load_dword v250, v[248:249], off
	global_load_dword v250, v[248:249], off offset:256
	v_add_co_u32_e32 v248, vcc, 0x90000, v246
	s_nop 1
	v_addc_co_u32_e32 v249, vcc, 0, v247, vcc
	global_load_dword v250, v[248:249], off
	global_load_dword v250, v[248:249], off offset:256
	v_add_co_u32_e32 v248, vcc, 0xa0000, v246
	s_nop 1
	v_addc_co_u32_e32 v249, vcc, 0, v247, vcc
	global_load_dword v250, v[248:249], off
	global_load_dword v250, v[248:249], off offset:256
	v_add_co_u32_e32 v248, vcc, 0xb0000, v246
	s_nop 1
	v_addc_co_u32_e32 v249, vcc, 0, v247, vcc
	global_load_dword v250, v[248:249], off
	global_load_dword v250, v[248:249], off offset:256
	v_and_b32_e32 v167, 64, v221
	v_xor_b32_e32 v166, 16, v221
	v_add_u32_e32 v167, 64, v167
	v_xor_b32_e32 v178, 32, v221
	v_cmp_lt_i32_e32 vcc, v166, v167
	s_waitcnt vmcnt(0)
	v_lshlrev_b32_e32 v180, 16, v170
	v_cndmask_b32_e32 v166, v221, v166, vcc
	v_cmp_lt_i32_e32 vcc, v178, v167
	v_and_b32_e32 v181, 0xffff0000, v170
	v_lshlrev_b32_e32 v170, 16, v171
	v_cndmask_b32_e32 v167, v221, v178, vcc
	v_lshl_add_u64 v[178:179], s[4:5], 0, v[158:159]
	v_lshl_add_u64 v[176:177], v[178:179], 0, v[176:177]
	v_lshlrev_b32_e32 v178, 16, v168
	v_and_b32_e32 v179, 0xffff0000, v168
	v_lshlrev_b32_e32 v168, 16, v169
	v_and_b32_e32 v169, 0xffff0000, v169
	v_and_b32_e32 v171, 0xffff0000, v171
	v_lshlrev_b32_e32 v182, 16, v172
	v_and_b32_e32 v183, 0xffff0000, v172
	v_lshlrev_b32_e32 v172, 16, v173
	v_and_b32_e32 v173, 0xffff0000, v173
	v_lshlrev_b32_e32 v184, 16, v174
	v_and_b32_e32 v185, 0xffff0000, v174
	v_lshlrev_b32_e32 v174, 16, v175
	v_and_b32_e32 v175, 0xffff0000, v175
	v_pk_add_f32 v[132:133], v[132:133], v[168:169]
	v_pk_add_f32 v[130:131], v[130:131], v[178:179]
	v_pk_add_f32 v[128:129], v[128:129], v[170:171]
	v_pk_add_f32 v[126:127], v[126:127], v[180:181]
	v_pk_add_f32 v[168:169], v[124:125], v[172:173]
	v_pk_add_f32 v[122:123], v[122:123], v[182:183]
	v_pk_add_f32 v[170:171], v[120:121], v[174:175]
	v_pk_add_f32 v[172:173], v[118:119], v[184:185]
	v_mul_f32_e32 v121, v131, v131
	v_mul_f32_e32 v124, v133, v133
	v_mul_f32_e32 v125, v127, v127
	v_mul_f32_e32 v174, v129, v129
	v_cvt_pk_bf16_f32 v118, v130, v131
	v_cvt_pk_bf16_f32 v119, v132, v133
	v_cvt_pk_bf16_f32 v120, v126, v127
	v_mul_f32_e32 v127, v123, v123
	v_mul_f32_e32 v131, v169, v169
	v_mul_f32_e32 v133, v173, v173
	v_mul_f32_e32 v175, v171, v171
	v_fmac_f32_e32 v121, v130, v130
	v_fmac_f32_e32 v124, v132, v132
	v_fmac_f32_e32 v125, v126, v126
	v_fmac_f32_e32 v174, v128, v128
	v_fmac_f32_e32 v127, v122, v122
	v_fmac_f32_e32 v131, v168, v168
	v_fmac_f32_e32 v133, v172, v172
	v_fmac_f32_e32 v175, v170, v170
	v_add_f32_e32 v121, v121, v124
	v_add_f32_e32 v124, v125, v174
	v_add_f32_e32 v125, v127, v131
	v_add_f32_e32 v126, v133, v175
	v_add_f32_e32 v121, v121, v124
	v_add_f32_e32 v124, v125, v126
	v_lshlrev_b32_e32 v166, 2, v166
	v_add_f32_e32 v126, v121, v124
	ds_bpermute_b32 v127, v166, v126
	v_cvt_pk_bf16_f32 v121, v128, v129
	global_store_dwordx4 v[176:177], v[118:121], off
	v_cvt_pk_bf16_f32 v124, v122, v123
	v_cvt_pk_bf16_f32 v125, v168, v169
	s_waitcnt lgkmcnt(0)
	s_nop 0
	v_add_f32_e32 v121, v126, v127
	v_lshlrev_b32_e32 v120, 2, v167
	ds_bpermute_b32 v122, v120, v121
	v_lshl_add_u64 v[118:119], v[154:155], 3, s[18:19]
	v_cvt_pk_bf16_f32 v126, v172, v173
	v_cvt_pk_bf16_f32 v127, v170, v171
	global_store_dwordx4 v[176:177], v[124:127], off offset:256
	s_and_saveexec_b64 s[4:5], s[38:39]
	s_cbranch_execz .LBB0_113
	s_waitcnt lgkmcnt(0)
	v_add_f32_e32 v121, v121, v122
	v_mul_f32_e32 v121, 0x4b800000, v121
	v_trunc_f32_e32 v121, v121
	v_mul_f32_e32 v122, 0x2f800000, v121
	v_floor_f32_e32 v123, v122
	v_fmac_f32_e32 v121, 0xcf800000, v123
	v_cvt_u32_f32_e32 v122, v121
	v_cvt_u32_f32_e32 v123, v123
	global_atomic_add_x2 v[118:119], v[122:123], off
